# stack: prep transposition tile issues both row loads before the first wait + wo loop scalar-base DMA with shared offset registers + T21 widened attn_c epilogue stores
# speedup vs baseline: 1.0099x; 1.0033x over previous
; DI void phase_prep(const Params& P, int l, char* shm) {
;     ...
;       const int tk = tl % nk, tn = tl / nk;
; #pragma unroll
;       for (int i = 0; i < 2; ++i) {
;         int idx = tid + i * 512, kk = idx >> 4, n4 = (idx & 15) * 4;
;         int n = tn * 64 + n4, k = tk * 64 + kk;
;         float4 v = make_float4(0.f, 0.f, 0.f, 0.f);
;         if (n < J.N) {
;           v = *(const float4*)(J.src + (size_t)k * J.ld + n);
;           if (J.rs) { float s = J.rs[k]; v.x *= s; v.y *= s; v.z *= s; v.w *= s; }
;         }
;         float* d = tile + kk * 65 + n4;
;         d[0] = v.x; d[1] = v.y; d[2] = v.z; d[3] = v.w;
.LBB0_92:
	s_or_saveexec_b64 s[60:61], s[58:59]
	s_mul_i32 s22, s22, s5
	s_sub_i32 s5, s96, s22
	s_lshl_b32 s58, s5, 6
	v_mov_b32_e32 v3, 0
	v_mov_b32_e32 v2, 0
	v_mov_b32_e32 v1, 0
	v_mov_b32_e32 v0, 0
	s_xor_b64 exec, exec, s[60:61]
	s_cbranch_execz .LBB0_27
	v_add_u32_e32 v6, s58, v12
	v_ashrrev_i32_e32 v7, 31, v6
	v_ashrrev_i32_e32 v5, 31, v4
	v_mul_lo_u32 v2, s54, v7
	v_mul_lo_u32 v3, s55, v6
	v_mad_u64_u32 v[0:1], s[22:23], s54, v6, 0
	v_lshl_add_u64 v[4:5], v[4:5], 2, s[56:57]
	v_add3_u32 v1, v1, v2, v3
	v_lshl_add_u64 v[0:1], v[0:1], 2, v[4:5]
	global_load_dwordx4 v[0:3], v[0:1], off
	v_add_u32_e32 v20, s58, v13
	v_ashrrev_i32_e32 v21, 31, v20
	v_mul_lo_u32 v22, s54, v21
	v_mul_lo_u32 v23, s55, v20
	v_mad_u64_u32 v[24:25], s[22:23], s54, v20, 0
	v_add3_u32 v25, v25, v22, v23
	v_lshl_add_u64 v[24:25], v[24:25], 2, v[4:5]
	global_load_dwordx4 v[24:27], v[24:25], off
	s_cmp_eq_u64 s[52:53], 0
	s_cbranch_scc1 .Lprep_nors
	v_lshl_add_u64 v[6:7], v[6:7], 2, s[52:53]
	global_load_dword v6, v[6:7], off
	v_lshl_add_u64 v[22:23], v[20:21], 2, s[52:53]
	global_load_dword v22, v[22:23], off
	s_waitcnt vmcnt(0)
	v_pk_mul_f32 v[0:1], v[0:1], v[6:7] op_sel_hi:[1,0]
	v_pk_mul_f32 v[2:3], v[2:3], v[6:7] op_sel_hi:[1,0]
	v_pk_mul_f32 v[24:25], v[24:25], v[22:23] op_sel_hi:[1,0]
	v_pk_mul_f32 v[26:27], v[26:27], v[22:23] op_sel_hi:[1,0]
.Lprep_nors:
	s_waitcnt vmcnt(0)
	ds_write2_b32 v14, v0, v1 offset1:1
	ds_write2_b32 v14, v2, v3 offset0:2 offset1:3
	v_mov_b32_e32 v0, v24
	v_mov_b32_e32 v1, v25
	v_mov_b32_e32 v2, v26
	v_mov_b32_e32 v3, v27
	s_branch .LBB0_27

; DI int tid_() { int t = threadIdx.x; asm volatile("" : "+v"(t)); return t; }
; template <int MF, int NF, bool SWAP = true>
; DI void gemm_main(f32x4 (&acc)[MF][NF], const u16* __restrict__ Ab, int lda, const u16* __restrict__ Bb, int ldb,
;                   int K, char* shm) {
;   constexpr bool RING3 = (NF == 2);
;   constexpr int TILE_A = 32768, STAGE = RING3 ? 49152 : 65536;
;   const int tid = tid_(), wid = tid >> 6, lane = tid & 63, wr = wid >> 2, wc = wid & 3, fr = lane & 15,
;             fq = lane >> 4;
;   constexpr int AL = MF / 2;
;   int sR0, sC0;
;   stage_rc<2>(wid * 1024 + lane * 16, sR0, sC0);
; #pragma unroll
;   for (int m = 0; m < MF; ++m)
; #pragma unroll
;     for (int n = 0; n < NF; ++n) acc[m][n] = f32x4{0.f, 0.f, 0.f, 0.f};
;   const int nt = K >> 6;
;   const int pa0 = sR0 * lda + sC0, pb0 = sR0 * ldb + sC0;
;     ...
;   const int a_off = lds_byte<2>(fr, fq * 8) + wr * (MF * 2048);
;   const int b_off = lds_byte<2>(fr, fq * 8) + wc * (NF * 2048);
;   G_STAGE(0, 0);
;   if constexpr (RING3) {
;     if (nt > 1) { G_STAGE(1, 1); asm volatile("s_waitcnt vmcnt(6)" ::: "memory"); }
;     else asm volatile("s_waitcnt vmcnt(0)" ::: "memory");
;     asm volatile("s_waitcnt lgkmcnt(0)" ::: "memory");
;     __builtin_amdgcn_s_barrier();
;   } else {
;     asm volatile("s_waitcnt vmcnt(0)" ::: "memory");
;     __syncthreads();
;   }
.LBB0_144:
	s_ashr_i32 s0, s16, 31
	s_lshr_b32 s0, s0, 29
	s_add_i32 s0, s16, s0
	s_ashr_i32 s1, s0, 3
	s_and_b32 s0, s0, -8
	s_sub_i32 s0, s16, s0
	s_lshr_b32 s4, s0, 31
	s_or_b32 s4, s4, 64
	s_mul_i32 s0, s4, s0
	s_add_i32 s0, s0, s1
	s_ashr_i32 s1, s0, 31
	s_lshr_b32 s1, s1, 27
	s_add_i32 s1, s0, s1
	s_ashr_i32 s4, s1, 5
	s_lshl_b32 s4, s4, 3
	s_sub_i32 s5, 0x80, s4
	s_min_u32 s5, s5, 8
	s_andn2_b32 s1, s1, 31
	s_sub_i32 s10, s0, s1
	v_cvt_f32_ubyte0_e32 v1, s5
	v_cvt_f32_i32_e32 v0, s10
	v_rcp_iflag_f32_e32 v2, v1
	s_ashr_i32 s0, s10, 30
	s_or_b32 s11, s0, 1
	v_mov_b32_e32 v10, v135
	v_mul_f32_e32 v2, v0, v2
	v_trunc_f32_e32 v2, v2
	v_fma_f32 v0, -v2, v1, v0
	v_cvt_i32_f32_e32 v2, v2
	v_cmp_ge_f32_e64 s[0:1], |v0|, v1
	s_and_b64 s[0:1], s[0:1], exec
	s_cselect_b32 s0, s11, 0
	v_readfirstlane_b32 s1, v2
	s_add_i32 s0, s1, s0
	s_lshl_b32 s18, s0, 24
	s_sext_i32_i8 s1, s0
	s_mul_i32 s0, s0, s5
	s_sub_i32 s0, s10, s0
	v_lshlrev_b32_e32 v0, 4, v10
	v_and_b32_e32 v2, 32, v10
	v_ashrrev_i32_e32 v11, 6, v10
	v_lshrrev_b32_e32 v3, 31, v10
	v_bitop3_b32 v0, v0, v2, 48 bitop3:0x6c
	s_sext_i32_i8 s0, s0
	v_add_u32_e32 v3, v11, v3
	v_lshrrev_b32_e32 v13, 1, v0
	v_lshlrev_b32_e32 v0, 8, v10
	s_add_i32 s4, s4, s0
	v_and_b32_e32 v1, 15, v10
	v_ashrrev_i32_e32 v12, 1, v3
	v_and_b32_e32 v3, 0x7fffffe, v3
	v_and_b32_e32 v14, 0x3c00, v0
	s_lshl_b32 s10, s4, 8
	v_sub_u32_e32 v3, v11, v3
	v_lshl_or_b32 v0, v12, 14, v14
	v_lshlrev_b32_e32 v15, 6, v1
	v_lshlrev_b32_e32 v1, 2, v10
	s_ashr_i32 s11, s10, 31
	v_lshl_add_u32 v0, v3, 5, v0
	v_and_b32_e32 v16, 32, v1
	v_lshlrev_b32_e32 v1, 6, v10
	s_lshl_b32 s12, s1, 8
	s_lshl_b64 s[0:1], s[10:11], 11
	v_or_b32_e32 v0, v0, v13
	v_and_b32_e32 v129, 0xffffc000, v1
	v_lshlrev_b32_e32 v1, 13, v11
	s_add_u32 s0, s14, s0
	v_lshlrev_b32_e32 v128, 10, v11
	v_and_b32_e32 v131, 0x6000, v1
	v_ashrrev_i32_e32 v1, 31, v0
	s_addc_u32 s1, s15, s1
	v_lshlrev_b64 v[2:3], 1, v[0:1]
	v_readfirstlane_b32 s11, v128
	v_lshl_add_u64 v[4:5], s[0:1], 0, v[2:3]
	s_mov_b32 m0, s11
	s_mov_b64 s[20:21], 0x20000
	v_add_u32_e32 v1, 0x2000, v128
	v_add_u32_e32 v0, 0x20000, v0
	global_load_lds_dwordx4 v[4:5], off
	v_lshl_add_u64 v[4:5], v[2:3], 0, s[20:21]
	v_readfirstlane_b32 s11, v1
	v_ashrrev_i32_e32 v1, 31, v0
	v_add_u32_e32 v8, 0x4000, v128
	v_lshl_add_u64 v[6:7], s[0:1], 0, v[4:5]
	s_mov_b32 m0, s11
	v_lshlrev_b64 v[0:1], 1, v[0:1]
	v_readfirstlane_b32 s11, v8
	s_ashr_i32 s13, s12, 31
	global_load_lds_dwordx4 v[6:7], off
	v_lshl_add_u64 v[6:7], s[0:1], 0, v[0:1]
	s_mov_b32 m0, s11
	v_add_u32_e32 v17, 0x6000, v128
	s_lshl_b64 s[4:5], s[12:13], 11
	global_load_lds_dwordx4 v[6:7], off
	v_lshl_add_u64 v[6:7], v[2:3], 0, s[86:87]
	v_readfirstlane_b32 s11, v17
	s_add_u32 s4, s6, s4
	v_lshl_add_u64 v[8:9], s[0:1], 0, v[6:7]
	s_mov_b32 m0, s11
	s_addc_u32 s5, s7, s5
	global_load_lds_dwordx4 v[8:9], off
	v_and_b32_e32 v8, 48, v10
	s_add_u32 s4, s4, 0x500000
	v_bitop3_b32 v132, v15, v16, v8 bitop3:0x36
	v_add_u32_e32 v8, 0x8000, v128
	s_addc_u32 s5, s5, 0
	v_readfirstlane_b32 s11, v8
	v_lshl_add_u64 v[2:3], s[4:5], 0, v[2:3]
	s_mov_b32 m0, s11
	v_lshl_add_u64 v[0:1], s[4:5], 0, v[0:1]
	global_load_lds_dwordx4 v[2:3], off
	v_lshl_add_u64 v[2:3], s[4:5], 0, v[4:5]
	v_add_u32_e32 v4, 0xa000, v128
	s_mov_b32 s17, 0
	v_readfirstlane_b32 s11, v4
	s_mov_b32 m0, s11
	s_mov_b32 s13, 0
	global_load_lds_dwordx4 v[2:3], off
	v_add_u32_e32 v2, 0xc000, v128
	s_nop 0
	v_readfirstlane_b32 s11, v2
	v_add_u32_e32 v2, 0xe000, v128
	s_mov_b32 m0, s11
	v_readfirstlane_b32 s11, v2
	global_load_lds_dwordx4 v[0:1], off
	v_lshl_add_u64 v[0:1], s[4:5], 0, v[6:7]
	s_mov_b32 m0, s11
	s_mov_b32 s11, 0
	global_load_lds_dwordx4 v[0:1], off
	v_mul_lo_u32 v0, v12, s70
	s_waitcnt vmcnt(0)
	v_or_b32_e32 v0, v13, v0
	v_lshlrev_b32_e32 v1, 5, v11
	v_add3_u32 v136, v0, v14, v1
	v_mov_b32_e32 v0, 0
	v_mov_b32_e32 v1, v0
	v_mov_b32_e32 v2, v0
	v_mov_b32_e32 v3, v0
	v_mov_b32_e32 v4, v0
	v_mov_b32_e32 v5, v0
	v_mov_b32_e32 v6, v0
	v_mov_b32_e32 v7, v0
	v_mov_b32_e32 v8, v0
	v_mov_b32_e32 v9, v0
	v_mov_b32_e32 v10, v0
	v_mov_b32_e32 v11, v0
	v_mov_b32_e32 v12, v0
	v_mov_b32_e32 v13, v0
	v_mov_b32_e32 v14, v0
	v_mov_b32_e32 v15, v0
	v_mov_b32_e32 v16, v0
	v_mov_b32_e32 v17, v0
	v_mov_b32_e32 v18, v0
	v_mov_b32_e32 v19, v0
	v_mov_b32_e32 v20, v0
	v_mov_b32_e32 v21, v0
	v_mov_b32_e32 v22, v0
	v_mov_b32_e32 v23, v0
	v_mov_b32_e32 v24, v0
	v_mov_b32_e32 v25, v0
	v_mov_b32_e32 v26, v0
	v_mov_b32_e32 v27, v0
	v_mov_b32_e32 v28, v0
	v_mov_b32_e32 v29, v0
	v_mov_b32_e32 v30, v0
	v_mov_b32_e32 v31, v0
	v_mov_b32_e32 v32, v0
	v_mov_b32_e32 v33, v0
	v_mov_b32_e32 v34, v0
	v_mov_b32_e32 v35, v0
	v_mov_b32_e32 v36, v0
	v_mov_b32_e32 v37, v0
	v_mov_b32_e32 v38, v0
	v_mov_b32_e32 v39, v0
	v_mov_b32_e32 v40, v0
	v_mov_b32_e32 v41, v0
	v_mov_b32_e32 v42, v0
	v_mov_b32_e32 v43, v0
	v_mov_b32_e32 v44, v0
	v_mov_b32_e32 v45, v0
	v_mov_b32_e32 v46, v0
	v_mov_b32_e32 v47, v0
	v_mov_b32_e32 v48, v0
	v_mov_b32_e32 v49, v0
	v_mov_b32_e32 v50, v0
	v_mov_b32_e32 v51, v0
	v_mov_b32_e32 v52, v0
	v_mov_b32_e32 v53, v0
	v_mov_b32_e32 v54, v0
	v_mov_b32_e32 v55, v0
	v_mov_b32_e32 v56, v0
	v_mov_b32_e32 v57, v0
	v_mov_b32_e32 v58, v0
	v_mov_b32_e32 v59, v0
	v_mov_b32_e32 v60, v0
	v_mov_b32_e32 v61, v0
	v_mov_b32_e32 v62, v0
	v_mov_b32_e32 v63, v0
	v_mov_b32_e32 v64, v0
	v_mov_b32_e32 v65, v0
	v_mov_b32_e32 v66, v0
	v_mov_b32_e32 v67, v0
	v_mov_b32_e32 v68, v0
	v_mov_b32_e32 v69, v0
	v_mov_b32_e32 v70, v0
	v_mov_b32_e32 v71, v0
	v_mov_b32_e32 v72, v0
	v_mov_b32_e32 v73, v0
	v_mov_b32_e32 v74, v0
	v_mov_b32_e32 v75, v0
	v_mov_b32_e32 v76, v0
	v_mov_b32_e32 v77, v0
	v_mov_b32_e32 v78, v0
	v_mov_b32_e32 v79, v0
	v_mov_b32_e32 v80, v0
	v_mov_b32_e32 v81, v0
	v_mov_b32_e32 v82, v0
	v_mov_b32_e32 v83, v0
	v_mov_b32_e32 v84, v0
	v_mov_b32_e32 v85, v0
	v_mov_b32_e32 v86, v0
	v_mov_b32_e32 v87, v0
	v_mov_b32_e32 v88, v0
	v_mov_b32_e32 v89, v0
	v_mov_b32_e32 v90, v0
	v_mov_b32_e32 v91, v0
	v_mov_b32_e32 v92, v0
	v_mov_b32_e32 v93, v0
	v_mov_b32_e32 v94, v0
	v_mov_b32_e32 v95, v0
	v_mov_b32_e32 v96, v0
	v_mov_b32_e32 v97, v0
	v_mov_b32_e32 v98, v0
	v_mov_b32_e32 v99, v0
	v_mov_b32_e32 v100, v0
	v_mov_b32_e32 v101, v0
	v_mov_b32_e32 v102, v0
	v_mov_b32_e32 v103, v0
	v_mov_b32_e32 v104, v0
	v_mov_b32_e32 v105, v0
	v_mov_b32_e32 v106, v0
	v_mov_b32_e32 v107, v0
	v_mov_b32_e32 v108, v0
	v_mov_b32_e32 v109, v0
	v_mov_b32_e32 v110, v0
	v_mov_b32_e32 v111, v0
	v_mov_b32_e32 v112, v0
	v_mov_b32_e32 v113, v0
	v_mov_b32_e32 v114, v0
	v_mov_b32_e32 v115, v0
	v_mov_b32_e32 v116, v0
	v_mov_b32_e32 v117, v0
	v_mov_b32_e32 v118, v0
	v_mov_b32_e32 v119, v0
	v_mov_b32_e32 v120, v0
	v_mov_b32_e32 v121, v0
	v_mov_b32_e32 v122, v0
	v_mov_b32_e32 v123, v0
	v_mov_b32_e32 v124, v0
	v_mov_b32_e32 v125, v0
	v_mov_b32_e32 v126, v0
	v_mov_b32_e32 v127, v0
	s_waitcnt vmcnt(0) lgkmcnt(0)
	s_barrier
	s_nop 0
	s_branch .LBB0_146

; #define LDB_(dst, ks) _Pragma("unroll") for (int n = 0; n < 4; ++n) dst[n] = *(const bf16x8*)(sB + b_off + n * 2048 + (ks) * 1024)
; #define LDA_(dst, ks, h) _Pragma("unroll") for (int m = 0; m < 4; ++m) dst[m] = *(const bf16x8*)(sA + a_off + ((h) * 4 + m) * 2048 + (ks) * 1024)
; #define MMA_(A, B, h) _Pragma("unroll") for (int m = 0; m < 4; ++m) _Pragma("unroll") for (int n = 0; n < 4; ++n) \
;       acc[(h) * 4 + m][n] = SWAP ? MFMA16(B[n], A[m], acc[(h) * 4 + m][n]) : MFMA16(A[m], B[n], acc[(h) * 4 + m][n])
; template <int MF, int NF, bool SWAP = true>
; DI void gemm_main(f32x4 (&acc)[MF][NF], const u16* __restrict__ Ab, int lda, const u16* __restrict__ Bb, int ldb,
;                   int K, char* shm) {
;     ...
;   for (int t = 0; t < nt; ++t) {
;     const int cur = RING3 ? cur3 : (t & 1);
;     if constexpr (RING3) {
;       if (t + 2 < nt) G_STAGE(nxt3, t + 2);
;     } else {
;       if (t + 1 < nt) G_STAGE(cur ^ 1, t + 1);
;     }
;     const char* sA = shm + cur * STAGE;
;     const char* sB = sA + TILE_A;
;     if constexpr (MF == 8 && NF == 4) {
;       bf16x8 B0[4], B1[4], A0[4], A1[4], A2[4], A3[4];
;     ...
;       LDB_(B0, 0); LDA_(A0, 0, 0);
;       LDA_(A1, 0, 1); MMA_(A0, B0, 0);
;       LDB_(B1, 1); LDA_(A2, 1, 0); MMA_(A1, B0, 1);
;       LDA_(A3, 1, 1); MMA_(A2, B1, 0);
;       MMA_(A3, B1, 1);
.LBB0_874:
	s_and_b32 s23, s21, 0x10000
	s_cmp_gt_u32 s22, 14
	s_cbranch_scc1 .Lg_rot874_last
	s_cmp_eq_u32 s22, 0
	s_cbranch_scc1 .Lg_rot874_first
	v_mfma_f32_16x16x32_bf16 v[60:63], v[218:221], v[222:225], v[60:63]
	s_xor_b32 s24, s23, 0x10000
	v_add_u32_e32 v195, s24, v148
	v_mfma_f32_16x16x32_bf16 v[56:59], v[226:229], v[222:225], v[56:59]
	s_nop 0
	v_readfirstlane_b32 s24, v195
	s_nop 1
	s_add_u32 m0, s24, 0x0
	v_mfma_f32_16x16x32_bf16 v[52:55], v[230:233], v[222:225], v[52:55]
	global_load_lds_dwordx4 v255, s[98:99]
	s_add_u32 m0, s24, 0x2000
	v_mfma_f32_16x16x32_bf16 v[48:51], v[234:237], v[222:225], v[48:51]
	global_load_lds_dwordx4 v254, s[98:99]
	s_add_u32 m0, s24, 0x4000
	v_mfma_f32_16x16x32_bf16 v[44:47], v[218:221], v[238:241], v[44:47]
	global_load_lds_dwordx4 v251, s[98:99]
	s_add_u32 m0, s24, 0x6000
	v_mfma_f32_16x16x32_bf16 v[40:43], v[226:229], v[238:241], v[40:43]
	global_load_lds_dwordx4 v250, s[98:99]
	s_add_u32 m0, s24, 0x8000
	v_mfma_f32_16x16x32_bf16 v[36:39], v[230:233], v[238:241], v[36:39]
	global_load_lds_dwordx4 v255, s[100:101]
	s_add_u32 m0, s24, 0xa000
	v_mfma_f32_16x16x32_bf16 v[32:35], v[234:237], v[238:241], v[32:35]
	global_load_lds_dwordx4 v254, s[100:101]
	s_add_u32 m0, s24, 0xc000
	v_mfma_f32_16x16x32_bf16 v[28:31], v[218:221], v[242:245], v[28:31]
	global_load_lds_dwordx4 v251, s[100:101]
	s_add_u32 m0, s24, 0xe000
	v_mfma_f32_16x16x32_bf16 v[24:27], v[226:229], v[242:245], v[24:27]
	global_load_lds_dwordx4 v250, s[100:101]
	v_mfma_f32_16x16x32_bf16 v[16:19], v[230:233], v[242:245], v[16:19]
	s_add_u32 s98, s98, 0x80
	s_addc_u32 s99, s99, 0
	s_add_u32 s100, s100, 0x80
	s_addc_u32 s101, s101, 0
	v_add_u32_e32 v153, s23, v151
	v_add_u32_e32 v194, v153, v150
	ds_read_b128 v[154:157], v194 offset:32768
	ds_read_b128 v[158:161], v194 offset:34816
	ds_read_b128 v[162:165], v194 offset:36864
	ds_read_b128 v[166:169], v194 offset:38912
	v_add_u32_e32 v153, v153, v149
	ds_read_b128 v[170:173], v153
	ds_read_b128 v[174:177], v153 offset:2048
	ds_read_b128 v[178:181], v153 offset:4096
	ds_read_b128 v[182:185], v153 offset:6144
	ds_read_b128 v[186:189], v153 offset:8192
	v_mfma_f32_16x16x32_bf16 v[12:15], v[234:237], v[242:245], v[12:15]
	v_mfma_f32_16x16x32_bf16 v[8:11], v[218:221], v[246:249], v[8:11]
	v_mfma_f32_16x16x32_bf16 v[4:7], v[226:229], v[246:249], v[4:7]
	v_mfma_f32_16x16x32_bf16 v[0:3], v[230:233], v[246:249], v[0:3]
	v_mfma_f32_16x16x32_bf16 v[20:23], v[234:237], v[246:249], v[20:23]
	s_branch .Lg_rot874_main
.Lg_rot874_first:
	v_add_u32_e32 v190, s11, v152
	s_xor_b32 s24, s23, 0x10000
	v_add_u32_e32 v192, 64, v190
	v_add_u32_e32 v195, s24, v148
	v_ashrrev_i32_e32 v193, 31, v192
	v_lshlrev_b64 v[192:193], 1, v[192:193]
	v_readfirstlane_b32 s24, v195
	v_lshl_add_u64 v[196:197], s[12:13], 0, v[192:193]
	s_mov_b32 m0, s24
	v_add_u32_e32 v198, 0x2000, v195
	global_load_lds_dwordx4 v[196:197], off
	v_subrev_u32_e32 v255, s12, v196
	v_add_u32_e32 v196, 0x10040, v190
	v_ashrrev_i32_e32 v197, 31, v196
	v_lshlrev_b64 v[196:197], 1, v[196:197]
	v_readfirstlane_b32 s24, v198
	v_lshl_add_u64 v[200:201], s[12:13], 0, v[196:197]
	s_mov_b32 m0, s24
	v_add_u32_e32 v191, 0x4000, v195
	global_load_lds_dwordx4 v[200:201], off
	v_subrev_u32_e32 v254, s12, v200
	v_add_u32_e32 v200, 0x20040, v190
	v_ashrrev_i32_e32 v201, 31, v200
	v_lshlrev_b64 v[200:201], 1, v[200:201]
	v_readfirstlane_b32 s24, v191
	v_lshl_add_u64 v[198:199], s[12:13], 0, v[200:201]
	s_mov_b32 m0, s24
	v_add_u32_e32 v217, 0x6000, v195
	global_load_lds_dwordx4 v[198:199], off
	v_subrev_u32_e32 v251, s12, v198
	v_add_u32_e32 v198, 0x30040, v190
	v_ashrrev_i32_e32 v199, 31, v198
	v_lshlrev_b64 v[198:199], 1, v[198:199]
	v_readfirstlane_b32 s24, v217
	v_lshl_add_u64 v[190:191], s[12:13], 0, v[198:199]
	s_mov_b32 m0, s24
	v_lshl_add_u64 v[192:193], s[14:15], 0, v[192:193]
	global_load_lds_dwordx4 v[190:191], off
	v_subrev_u32_e32 v250, s12, v190
	v_add_u32_e32 v190, 0x8000, v195
	s_nop 0
	v_readfirstlane_b32 s24, v190
	s_mov_b32 m0, s24
	s_nop 0
	global_load_lds_dwordx4 v[192:193], off
	v_lshl_add_u64 v[192:193], s[14:15], 0, v[196:197]
	v_add_u32_e32 v196, 0xa000, v195
	s_nop 0
	v_readfirstlane_b32 s24, v196
	v_add_u32_e32 v196, 0xc000, v195
	s_mov_b32 m0, s24
	v_readfirstlane_b32 s24, v196
	v_add_u32_e32 v195, 0xe000, v195
	global_load_lds_dwordx4 v[192:193], off
	v_lshl_add_u64 v[192:193], s[14:15], 0, v[200:201]
	s_mov_b32 m0, s24
	v_readfirstlane_b32 s24, v195
	global_load_lds_dwordx4 v[192:193], off
	v_lshl_add_u64 v[192:193], s[14:15], 0, v[198:199]
	s_mov_b32 m0, s24
	s_nop 0
	global_load_lds_dwordx4 v[192:193], off
	s_add_u32 s98, s12, 0x80
	s_addc_u32 s99, s13, 0
	s_add_u32 s100, s14, 0x80
	s_addc_u32 s101, s15, 0
	v_add_u32_e32 v153, s23, v151
	v_add_u32_e32 v194, v153, v150
	ds_read_b128 v[154:157], v194 offset:32768
	ds_read_b128 v[158:161], v194 offset:34816
	ds_read_b128 v[162:165], v194 offset:36864
	ds_read_b128 v[166:169], v194 offset:38912
	v_add_u32_e32 v153, v153, v149
	ds_read_b128 v[170:173], v153
	ds_read_b128 v[174:177], v153 offset:2048
	ds_read_b128 v[178:181], v153 offset:4096
	ds_read_b128 v[182:185], v153 offset:6144
	ds_read_b128 v[186:189], v153 offset:8192
	s_branch .Lg_rot874_main
.Lg_rot874_last:
	v_add_u32_e32 v153, s23, v151
	v_add_u32_e32 v194, v153, v150
	ds_read_b128 v[154:157], v194 offset:32768
	ds_read_b128 v[158:161], v194 offset:34816
	ds_read_b128 v[162:165], v194 offset:36864
	ds_read_b128 v[166:169], v194 offset:38912
	v_add_u32_e32 v153, v153, v149
	ds_read_b128 v[170:173], v153
	ds_read_b128 v[174:177], v153 offset:2048
	ds_read_b128 v[178:181], v153 offset:4096
	ds_read_b128 v[182:185], v153 offset:6144
	ds_read_b128 v[186:189], v153 offset:8192
	v_mfma_f32_16x16x32_bf16 v[60:63], v[218:221], v[222:225], v[60:63]
	v_mfma_f32_16x16x32_bf16 v[56:59], v[226:229], v[222:225], v[56:59]
	v_mfma_f32_16x16x32_bf16 v[52:55], v[230:233], v[222:225], v[52:55]
	v_mfma_f32_16x16x32_bf16 v[48:51], v[234:237], v[222:225], v[48:51]
	v_mfma_f32_16x16x32_bf16 v[44:47], v[218:221], v[238:241], v[44:47]
	v_mfma_f32_16x16x32_bf16 v[40:43], v[226:229], v[238:241], v[40:43]
	v_mfma_f32_16x16x32_bf16 v[36:39], v[230:233], v[238:241], v[36:39]
	v_mfma_f32_16x16x32_bf16 v[32:35], v[234:237], v[238:241], v[32:35]
	v_mfma_f32_16x16x32_bf16 v[28:31], v[218:221], v[242:245], v[28:31]
	v_mfma_f32_16x16x32_bf16 v[24:27], v[226:229], v[242:245], v[24:27]
	v_mfma_f32_16x16x32_bf16 v[16:19], v[230:233], v[242:245], v[16:19]
	v_mfma_f32_16x16x32_bf16 v[12:15], v[234:237], v[242:245], v[12:15]
	v_mfma_f32_16x16x32_bf16 v[8:11], v[218:221], v[246:249], v[8:11]
	v_mfma_f32_16x16x32_bf16 v[4:7], v[226:229], v[246:249], v[4:7]
	v_mfma_f32_16x16x32_bf16 v[0:3], v[230:233], v[246:249], v[0:3]
	v_mfma_f32_16x16x32_bf16 v[20:23], v[234:237], v[246:249], v[20:23]
